# stick-breaking attention loop: removed 32 per-tile NaN-canonicalising v_max (v_min reads the score directly)
# speedup vs baseline: 1.0030x; 1.0030x over previous
; __device__ __forceinline__ int crow(int r, int hi) { return (r & 3) + 8 * (r >> 2) + 4 * hi; }
; #define MFMA32(a, b, c) __builtin_amdgcn_mfma_f32_32x32x16_bf16((a), (b), (c), 0, 0, 0)
; __device__ __forceinline__ void sb_unit(int b, int h, int qblk, const bf16_t* SQ, const bf16_t* SK, const bf16_t* SV, bf16_t* ATT, LAS unsigned char* wl, int lane) {
;     ...
;         f32x16 p0 = {}, p1 = {};
; #pragma unroll
;         for (int d0 = 0; d0 < 4; ++d0) { p0 = MFMA32(ka[2 * d0], qf[d0], p0); p1 = MFMA32(ka[2 * d0 + 1], qf[d0], p1); }
;         const bool diag = (jt == jd);
;         f32x16 L0, L1;
; #pragma unroll
;         for (int r = 0; r < 16; ++r) {
;             { const float z = p0[r], tt = __builtin_amdgcn_exp2f(-__builtin_fabsf(z)), uu = __builtin_amdgcn_logf(1.0f + tt), ls = __builtin_fminf(z, 0.f) - uu;
;               const bool ok = !diag || (k0 + crow(r, hh) < qi); L0[r] = ok ? (ls - z) : 0.f; p0[r] = ok ? ls : -1e30f; }
;             { const float z = p1[r], tt = __builtin_amdgcn_exp2f(-__builtin_fabsf(z)), uu = __builtin_amdgcn_logf(1.0f + tt), ls = __builtin_fminf(z, 0.f) - uu;
;               const bool ok = !diag || (k0 + 32 + crow(r, hh) < qi); L1[r] = ok ? (ls - z) : 0.f; p1[r] = ok ? ls : -1e30f; }
.LBB0_457:
	s_waitcnt vmcnt(7)
	v_mfma_f32_32x32x16_bf16 v[48:63], v[32:35], v[64:67], 0
	s_cmp_lg_u32 s82, 0
	v_add_u32_e32 v183, s82, v163
	s_cselect_b64 s[70:71], -1, 0
	v_cmp_lt_u32_e32 vcc, v183, v173
	s_or_b64 s[6:7], s[70:71], vcc
	s_waitcnt vmcnt(1)
	v_mfma_f32_32x32x16_bf16 v[32:47], v[36:39], v[64:67], 0
	v_mfma_f32_32x32x16_bf16 v[48:63], v[120:123], v[68:71], v[48:63]
	v_mfma_f32_32x32x16_bf16 v[32:47], v[124:127], v[68:71], v[32:47]
	v_mfma_f32_32x32x16_bf16 v[48:63], v[132:135], v[72:75], v[48:63]
	v_mfma_f32_32x32x16_bf16 v[32:47], v[116:119], v[72:75], v[32:47]
	v_add_u32_e32 v119, 32, v183
	v_cmp_lt_u32_e32 vcc, v119, v173
	s_or_b64 s[8:9], s[70:71], vcc
	v_mfma_f32_32x32x16_bf16 v[48:63], v[128:131], v[76:79], v[48:63]
	s_waitcnt vmcnt(0)
	v_mfma_f32_32x32x16_bf16 v[32:47], v[112:115], v[76:79], v[32:47]
	s_nop 9
	v_exp_f32_e64 v120, -|v48|
	v_min_f32_e32 v117, 0, v48
	v_exp_f32_e64 v114, -|v49|
	v_add_f32_e32 v116, 1.0, v120
	v_log_f32_e32 v116, v116
	v_exp_f32_e64 v112, -|v32|
	v_sub_f32_e32 v117, v117, v116
	v_sub_f32_e32 v48, v117, v48
	v_cndmask_b32_e64 v113, 0, v48, s[6:7]
	v_add_f32_e32 v48, 1.0, v112
	v_log_f32_e32 v48, v48
	v_min_f32_e32 v112, 0, v32
	v_sub_f32_e32 v118, v112, v48
	v_add_f32_e32 v48, 1.0, v114
	v_log_f32_e32 v48, v48
	v_sub_f32_e32 v32, v118, v32
	v_cndmask_b32_e64 v112, 0, v32, s[8:9]
	v_min_f32_e32 v32, 0, v49
	v_sub_f32_e32 v119, v32, v48
	v_exp_f32_e64 v32, -|v33|
	v_add_u32_e32 v48, 1, v183
	v_cmp_lt_u32_e32 vcc, v48, v173
	v_sub_f32_e32 v48, v119, v49
	v_add_f32_e32 v32, 1.0, v32
	v_log_f32_e32 v32, v32
	s_or_b64 s[10:11], s[70:71], vcc
	v_cndmask_b32_e64 v114, 0, v48, s[10:11]
	v_min_f32_e32 v48, 0, v33
	v_sub_f32_e32 v120, v48, v32
	v_exp_f32_e64 v32, -|v50|
	v_add_u32_e32 v48, 33, v183
	v_cmp_lt_u32_e32 vcc, v48, v173
	v_sub_f32_e32 v33, v120, v33
	v_add_f32_e32 v32, 1.0, v32
	v_log_f32_e32 v48, v32
	s_or_b64 s[12:13], s[70:71], vcc
	v_cndmask_b32_e64 v32, 0, v33, s[12:13]
	v_min_f32_e32 v33, 0, v50
	v_sub_f32_e32 v121, v33, v48
	v_exp_f32_e64 v33, -|v34|
	v_add_u32_e32 v48, 2, v183
	v_cmp_lt_u32_e32 vcc, v48, v173
	v_sub_f32_e32 v48, v121, v50
	v_add_f32_e32 v33, 1.0, v33
	v_log_f32_e32 v33, v33
	s_or_b64 s[14:15], s[70:71], vcc
	v_cndmask_b32_e64 v115, 0, v48, s[14:15]
	v_min_f32_e32 v48, 0, v34
	v_sub_f32_e32 v122, v48, v33
	v_exp_f32_e64 v33, -|v51|
	v_add_u32_e32 v48, 34, v183
	v_cmp_lt_u32_e32 vcc, v48, v173
	v_add_f32_e32 v33, 1.0, v33
	v_log_f32_e32 v33, v33
	v_min_f32_e32 v48, 0, v51
	s_or_b64 s[16:17], s[70:71], vcc
	v_sub_f32_e32 v123, v48, v33
	v_exp_f32_e64 v33, -|v35|
	v_add_u32_e32 v48, 3, v183
	v_cmp_lt_u32_e32 vcc, v48, v173
	v_sub_f32_e32 v48, v123, v51
	v_add_f32_e32 v33, 1.0, v33
	v_log_f32_e32 v33, v33
	s_or_b64 s[18:19], s[70:71], vcc
	v_cndmask_b32_e64 v116, 0, v48, s[18:19]
	v_min_f32_e32 v48, 0, v35
	v_sub_f32_e32 v125, v48, v33
	v_exp_f32_e64 v33, -|v52|
	v_add_u32_e32 v48, 35, v183
	v_cmp_lt_u32_e32 vcc, v48, v173
	v_sub_f32_e32 v35, v125, v35
	v_add_f32_e32 v33, 1.0, v33
	v_log_f32_e32 v33, v33
	s_or_b64 s[20:21], s[70:71], vcc
	v_cndmask_b32_e64 v48, 0, v35, s[20:21]
	v_min_f32_e32 v35, 0, v52
	v_sub_f32_e32 v126, v35, v33
	v_exp_f32_e64 v33, -|v36|
	v_min_f32_e32 v49, 0, v36
	v_add_u32_e32 v35, 8, v183
	v_cmp_lt_u32_e32 vcc, v35, v173
	v_add_f32_e32 v33, 1.0, v33
	v_log_f32_e32 v33, v33
	s_or_b64 s[0:1], s[70:71], vcc
	v_sub_f32_e32 v35, v126, v52
	v_cndmask_b32_e64 v35, 0, v35, s[0:1]
	v_sub_f32_e32 v127, v49, v33
	v_exp_f32_e64 v33, -|v53|
	v_add_u32_e32 v49, 40, v183
	v_cmp_lt_u32_e32 vcc, v49, v173
	v_sub_f32_e32 v36, v127, v36
	v_add_f32_e32 v33, 1.0, v33
	v_log_f32_e32 v33, v33
	s_or_b64 s[24:25], s[70:71], vcc
	v_cndmask_b32_e64 v49, 0, v36, s[24:25]
	v_min_f32_e32 v36, 0, v53
	v_sub_f32_e32 v128, v36, v33
	v_exp_f32_e64 v33, -|v37|
	v_add_u32_e32 v36, 9, v183
	v_cmp_lt_u32_e32 vcc, v36, v173
	v_sub_f32_e32 v36, v128, v53
	v_add_f32_e32 v33, 1.0, v33
	v_log_f32_e32 v33, v33
	s_or_b64 s[26:27], s[70:71], vcc
	v_cndmask_b32_e64 v53, 0, v36, s[26:27]
	v_min_f32_e32 v36, 0, v37
	v_sub_f32_e32 v130, v36, v33
	v_exp_f32_e64 v33, -|v54|
	v_add_u32_e32 v36, 41, v183
	v_cmp_lt_u32_e32 vcc, v36, v173
	v_sub_f32_e32 v36, v130, v37
	v_add_f32_e32 v33, 1.0, v33
	v_log_f32_e32 v33, v33
	s_or_b64 s[28:29], s[70:71], vcc
	v_cndmask_b32_e64 v37, 0, v36, s[28:29]
	v_min_f32_e32 v36, 0, v54
	v_sub_f32_e32 v131, v36, v33
	v_exp_f32_e64 v33, -|v38|
	v_add_u32_e32 v36, 10, v183
	v_cmp_lt_u32_e32 vcc, v36, v173
	v_sub_f32_e32 v36, v131, v54
	v_add_f32_e32 v33, 1.0, v33
	v_log_f32_e32 v33, v33
	s_or_b64 s[30:31], s[70:71], vcc
	v_cndmask_b32_e64 v54, 0, v36, s[30:31]
	v_min_f32_e32 v36, 0, v38
	v_sub_f32_e32 v132, v36, v33
	v_exp_f32_e64 v33, -|v55|
	v_add_u32_e32 v36, 42, v183
	v_cmp_lt_u32_e32 vcc, v36, v173
	v_sub_f32_e32 v36, v132, v38
	v_add_f32_e32 v33, 1.0, v33
	v_log_f32_e32 v33, v33
	s_or_b64 s[34:35], s[70:71], vcc
	v_cndmask_b32_e64 v129, 0, v36, s[34:35]
	v_min_f32_e32 v36, 0, v55
	v_sub_f32_e32 v133, v36, v33
	v_exp_f32_e64 v33, -|v39|
	v_add_u32_e32 v36, 11, v183
	v_cmp_lt_u32_e32 vcc, v36, v173
	v_sub_f32_e32 v36, v133, v55
	v_add_f32_e32 v33, 1.0, v33
	v_log_f32_e32 v33, v33
	s_or_b64 s[36:37], s[70:71], vcc
	v_cndmask_b32_e64 v124, 0, v36, s[36:37]
	v_min_f32_e32 v36, 0, v39
	v_sub_f32_e32 v134, v36, v33
	v_exp_f32_e64 v33, -|v56|
	v_add_u32_e32 v36, 43, v183
	v_cmp_lt_u32_e32 vcc, v36, v173
	v_sub_f32_e32 v36, v134, v39
	v_add_f32_e32 v33, 1.0, v33
	v_log_f32_e32 v33, v33
	s_or_b64 s[38:39], s[70:71], vcc
	v_cndmask_b32_e64 v39, 0, v36, s[38:39]
	v_min_f32_e32 v36, 0, v56
	v_sub_f32_e32 v135, v36, v33
	v_exp_f32_e64 v33, -|v40|
	v_add_u32_e32 v36, 16, v183
; __device__ __forceinline__ int crow(int r, int hi) { return (r & 3) + 8 * (r >> 2) + 4 * hi; }
; __device__ __forceinline__ void sb_unit(int b, int h, int qblk, const bf16_t* SQ, const bf16_t* SK, const bf16_t* SV, bf16_t* ATT, LAS unsigned char* wl, int lane) {
;     ...
;         for (int r = 0; r < 16; ++r) {
;             { const float z = p0[r], tt = __builtin_amdgcn_exp2f(-__builtin_fabsf(z)), uu = __builtin_amdgcn_logf(1.0f + tt), ls = __builtin_fminf(z, 0.f) - uu;
;               const bool ok = !diag || (k0 + crow(r, hh) < qi); L0[r] = ok ? (ls - z) : 0.f; p0[r] = ok ? ls : -1e30f; }
;             { const float z = p1[r], tt = __builtin_amdgcn_exp2f(-__builtin_fabsf(z)), uu = __builtin_amdgcn_logf(1.0f + tt), ls = __builtin_fminf(z, 0.f) - uu;
;               const bool ok = !diag || (k0 + 32 + crow(r, hh) < qi); L1[r] = ok ? (ls - z) : 0.f; p1[r] = ok ? ls : -1e30f; }
;         }
;         float ob[8], pb[8];
; #pragma unroll
;         for (int g = 0; g < 4; ++g) { ob[g] = (L0[4 * g] + L0[4 * g + 1]) + (L0[4 * g + 2] + L0[4 * g + 3]); ob[4 + g] = (L1[4 * g] + L1[4 * g + 1]) + (L1[4 * g + 2] + L1[4 * g + 3]); }
; #pragma unroll
;         for (int g = 0; g < 8; ++g) pb[g] = __shfl_xor(ob[g], 32);
	v_cmp_lt_u32_e32 vcc, v36, v173
	v_sub_f32_e32 v36, v135, v56
	v_add_f32_e32 v33, 1.0, v33
	v_log_f32_e32 v33, v33
	s_or_b64 s[40:41], s[70:71], vcc
	v_cndmask_b32_e64 v38, 0, v36, s[40:41]
	v_min_f32_e32 v36, 0, v40
	v_sub_f32_e32 v136, v36, v33
	v_exp_f32_e64 v33, -|v57|
	v_add_u32_e32 v36, 48, v183
	v_cmp_lt_u32_e32 vcc, v36, v173
	v_sub_f32_e32 v36, v136, v40
	v_add_f32_e32 v33, 1.0, v33
	v_log_f32_e32 v33, v33
	s_or_b64 s[42:43], s[70:71], vcc
	v_cndmask_b32_e64 v40, 0, v36, s[42:43]
	v_min_f32_e32 v36, 0, v57
	v_sub_f32_e32 v137, v36, v33
	v_exp_f32_e64 v33, -|v41|
	v_add_u32_e32 v36, 17, v183
	v_cmp_lt_u32_e32 vcc, v36, v173
	v_sub_f32_e32 v36, v137, v57
	v_add_f32_e32 v33, 1.0, v33
	v_log_f32_e32 v33, v33
	s_or_b64 s[44:45], s[70:71], vcc
	v_cndmask_b32_e64 v55, 0, v36, s[44:45]
	v_min_f32_e32 v36, 0, v41
	v_sub_f32_e32 v138, v36, v33
	v_exp_f32_e64 v33, -|v58|
	v_add_u32_e32 v36, 49, v183
	v_cmp_lt_u32_e32 vcc, v36, v173
	v_sub_f32_e32 v36, v138, v41
	v_add_f32_e32 v33, 1.0, v33
	v_log_f32_e32 v33, v33
	s_or_b64 s[46:47], s[70:71], vcc
	v_cndmask_b32_e64 v52, 0, v36, s[46:47]
	v_min_f32_e32 v36, 0, v58
	v_sub_f32_e32 v140, v36, v33
	v_exp_f32_e64 v33, -|v42|
	v_add_u32_e32 v36, 18, v183
	v_cmp_lt_u32_e32 vcc, v36, v173
	v_sub_f32_e32 v36, v140, v58
	v_add_f32_e32 v33, 1.0, v33
	v_log_f32_e32 v33, v33
	s_or_b64 s[48:49], s[70:71], vcc
	v_cndmask_b32_e64 v57, 0, v36, s[48:49]
	v_min_f32_e32 v36, 0, v42
	v_sub_f32_e32 v141, v36, v33
	v_exp_f32_e64 v33, -|v59|
	v_add_u32_e32 v36, 50, v183
	v_cmp_lt_u32_e32 vcc, v36, v173
	v_sub_f32_e32 v36, v141, v42
	v_add_f32_e32 v33, 1.0, v33
	v_log_f32_e32 v33, v33
	s_or_b64 s[50:51], s[70:71], vcc
	v_cndmask_b32_e64 v139, 0, v36, s[50:51]
	v_min_f32_e32 v36, 0, v59
	v_sub_f32_e32 v142, v36, v33
	v_exp_f32_e64 v33, -|v43|
	v_add_u32_e32 v36, 19, v183
	v_cmp_lt_u32_e32 vcc, v36, v173
	v_sub_f32_e32 v36, v142, v59
	v_add_f32_e32 v33, 1.0, v33
	v_log_f32_e32 v33, v33
	s_or_b64 s[52:53], s[70:71], vcc
	v_cndmask_b32_e64 v58, 0, v36, s[52:53]
	v_min_f32_e32 v36, 0, v43
	v_sub_f32_e32 v143, v36, v33
	v_exp_f32_e64 v33, -|v60|
	v_add_u32_e32 v36, 51, v183
	v_cmp_lt_u32_e32 vcc, v36, v173
	v_sub_f32_e32 v36, v143, v43
	v_add_f32_e32 v33, 1.0, v33
	v_log_f32_e32 v33, v33
	s_or_b64 s[54:55], s[70:71], vcc
	v_cndmask_b32_e64 v59, 0, v36, s[54:55]
	v_min_f32_e32 v36, 0, v60
	v_sub_f32_e32 v175, v36, v33
	v_exp_f32_e64 v33, -|v44|
	v_add_u32_e32 v36, 24, v183
	v_cmp_lt_u32_e32 vcc, v36, v173
	v_sub_f32_e32 v36, v175, v60
	v_add_f32_e32 v33, 1.0, v33
	v_log_f32_e32 v33, v33
	s_or_b64 s[56:57], s[70:71], vcc
	v_cndmask_b32_e64 v41, 0, v36, s[56:57]
	v_min_f32_e32 v36, 0, v44
	v_sub_f32_e32 v176, v36, v33
	v_exp_f32_e64 v33, -|v61|
	v_add_u32_e32 v36, 56, v183
	v_cmp_lt_u32_e32 vcc, v36, v173
	v_sub_f32_e32 v36, v176, v44
	v_add_f32_e32 v33, 1.0, v33
	v_log_f32_e32 v33, v33
	s_or_b64 s[58:59], s[70:71], vcc
	v_cndmask_b32_e64 v42, 0, v36, s[58:59]
	v_min_f32_e32 v36, 0, v61
	v_sub_f32_e32 v177, v36, v33
	v_exp_f32_e64 v33, -|v45|
	v_add_u32_e32 v36, 25, v183
	v_cmp_lt_u32_e32 vcc, v36, v173
	v_sub_f32_e32 v36, v177, v61
	v_add_f32_e32 v33, 1.0, v33
	v_log_f32_e32 v33, v33
	s_or_b64 s[60:61], s[70:71], vcc
	v_cndmask_b32_e64 v43, 0, v36, s[60:61]
	v_min_f32_e32 v36, 0, v45
	v_sub_f32_e32 v179, v36, v33
	v_exp_f32_e64 v33, -|v62|
	v_add_u32_e32 v36, 57, v183
	v_cmp_lt_u32_e32 vcc, v36, v173
	v_sub_f32_e32 v36, v179, v45
	v_add_f32_e32 v33, 1.0, v33
	v_log_f32_e32 v33, v33
	s_or_b64 s[62:63], s[70:71], vcc
	v_cndmask_b32_e64 v178, 0, v36, s[62:63]
	v_min_f32_e32 v36, 0, v62
	v_sub_f32_e32 v180, v36, v33
	v_exp_f32_e64 v33, -|v46|
	v_add_u32_e32 v36, 26, v183
	v_cmp_lt_u32_e32 vcc, v36, v173
	v_sub_f32_e32 v36, v180, v62
	v_add_f32_e32 v33, 1.0, v33
	v_log_f32_e32 v33, v33
	s_or_b64 s[64:65], s[70:71], vcc
	v_cndmask_b32_e64 v60, 0, v36, s[64:65]
	v_min_f32_e32 v36, 0, v46
	v_sub_f32_e32 v62, v36, v33
	v_exp_f32_e64 v33, -|v63|
	v_add_u32_e32 v36, 58, v183
	v_cmp_lt_u32_e32 vcc, v36, v173
	v_sub_f32_e32 v36, v62, v46
	v_add_f32_e32 v33, 1.0, v33
	v_log_f32_e32 v33, v33
	s_or_b64 s[66:67], s[70:71], vcc
	v_cndmask_b32_e64 v181, 0, v36, s[66:67]
	v_min_f32_e32 v36, 0, v63
	v_sub_f32_e32 v182, v36, v33
	v_exp_f32_e64 v33, -|v47|
	v_add_u32_e32 v36, 27, v183
	v_cmp_lt_u32_e32 vcc, v36, v173
	v_sub_f32_e32 v36, v182, v63
	v_add_f32_e32 v33, 1.0, v33
	v_log_f32_e32 v33, v33
	s_or_b64 s[68:69], s[70:71], vcc
	v_cndmask_b32_e64 v61, 0, v36, s[68:69]
	v_min_f32_e32 v36, 0, v47
	v_sub_f32_e32 v63, v36, v33
	v_add_u32_e32 v33, 59, v183
	v_cmp_lt_u32_e32 vcc, v33, v173
	v_sub_f32_e32 v33, v63, v47
	s_or_b64 s[70:71], s[70:71], vcc
	v_cndmask_b32_e64 v183, 0, v33, s[70:71]
	v_add_f32_e32 v33, v113, v114
	v_add_f32_e32 v36, v115, v116
	v_add_f32_e32 v56, v33, v36
	v_add_f32_e32 v33, v35, v53
	v_add_f32_e32 v35, v54, v124
	v_add_f32_e32 v36, v33, v35
	v_add_f32_e32 v33, v49, v37
	v_add_f32_e32 v35, v129, v39
	v_add_f32_e32 v113, v33, v35
	v_add_f32_e32 v33, v38, v55
	v_add_f32_e32 v35, v57, v58
	v_add_f32_e32 v38, v33, v35
	v_add_f32_e32 v33, v40, v52
	v_add_f32_e32 v35, v139, v59
	v_add_f32_e32 v35, v33, v35
	v_add_f32_e32 v33, v42, v178
	v_add_f32_e32 v40, v181, v183
	v_add_f32_e32 v40, v33, v40
	ds_bpermute_b32 v185, v214, v40
	ds_bpermute_b32 v184, v214, v35
	ds_bpermute_b32 v33, v214, v113
	v_sub_f32_e32 v34, v122, v34
	v_cndmask_b32_e64 v34, 0, v34, s[16:17]
	s_waitcnt lgkmcnt(2)
	v_add_f32_e32 v40, v40, v185
	v_add_f32_e32 v49, 0, v40
	s_waitcnt lgkmcnt(1)
	v_add_f32_e32 v35, v35, v184
	v_add_f32_e32 v50, v41, v43
	v_pk_add_f32 v[40:41], v[34:35], v[48:49]
	s_waitcnt lgkmcnt(0)
	v_pk_add_f32 v[44:45], v[112:113], v[32:33]
	v_add_f32_e32 v46, v60, v61
	v_pk_add_f32 v[44:45], v[44:45], v[40:41]
	ds_bpermute_b32 v47, v214, v44
	v_mov_b32_e32 v51, v44
	ds_bpermute_b32 v35, v214, v56
	ds_bpermute_b32 v40, v214, v36
	ds_bpermute_b32 v42, v214, v38
	s_waitcnt lgkmcnt(3)
	v_pk_add_f32 v[50:51], v[50:51], v[46:47]
	ds_bpermute_b32 v44, v214, v50
	s_andn2_b64 vcc, exec, s[74:75]
	s_cbranch_vccnz .LBB0_465
	s_waitcnt vmcnt(8)
	s_cbranch_execnz .LBB0_460
